# UQ/UKV gemm_phase end: counted vmcnt (only the last stores may stay in flight) instead of vmcnt(0)
# baseline (speedup 1.0000x reference)
; #define PG8_WAIT_V(n) asm volatile("s_waitcnt vmcnt(" #n ")" ::: "memory")
; #define PG8_BAR __builtin_amdgcn_s_barrier()
; template <class Epi, class Sched, bool ALIGN_EPI>
; __device__ __forceinline__ void gemm_phase(PG8_LAS unsigned char* lds, const Gemm g, const Sched& S, const Epi& E) {
;     ...
;     PG8_WAIT_V(0);
;     if constexpr (!ALIGN_EPI) { if (wr == 0) PG8_BAR; }
;     PG8_BAR;
.LBB0_112:
	s_waitcnt vmcnt(16)
	s_cmpk_gt_u32 s13, 0xff
	s_cbranch_scc1 .LBB0_114
	v_readlane_b32 vcc_lo, v255, 43
	s_mov_b32 vcc_hi, 0
	s_nop 1
	v_writelane_b32 v255, vcc_hi, 43
	s_cmp_eq_u32 vcc_lo, 1
	s_cbranch_scc1 .LBB0_114
	s_barrier

; #define PG8_WAIT_V(n) asm volatile("s_waitcnt vmcnt(" #n ")" ::: "memory")
; #define PG8_BAR __builtin_amdgcn_s_barrier()
; template <class Epi, class Sched, bool ALIGN_EPI>
; __device__ __forceinline__ void gemm_phase(PG8_LAS unsigned char* lds, const Gemm g, const Sched& S, const Epi& E) {
;     ...
;     PG8_WAIT_V(0);
;     if constexpr (!ALIGN_EPI) { if (wr == 0) PG8_BAR; }
;     PG8_BAR;
.LBB0_165:
	s_waitcnt vmcnt(3)
	v_readlane_b32 s2, v255, 16
	s_cmpk_gt_u32 s2, 0xff
	s_cbranch_scc1 .LBB0_167
	v_readlane_b32 s98, v255, 43
	s_mov_b32 s99, 0
	s_nop 1
	v_writelane_b32 v255, s99, 43
	s_cmp_eq_u32 s98, 1
	s_cbranch_scc1 .LBB0_167
	s_barrier
